# v68 + P3b's 16 tail units run inside the P1b phase on 16 workgroups (whose two dropped P1b units go to idle class-L workgroups of P2); P3b is exactly two rounds
# speedup vs baseline: 1.0154x; 1.0108x over previous
.Lp1be_ret:
	v_readlane_b32 s80, v254, 59
	v_readlane_b32 s83, v255, 6
	s_cmp_eq_u32 s98, 1
	s_cbranch_scc0 .Lp1be_done
	s_sub_u32 s101, s83, 0xd0
	s_cmp_gt_u32 s101, 31
	s_cbranch_scc1 .Lp1be_done
	s_lshl_b32 s99, s101, 1
	s_lshr_b32 s100, s101, 4
	s_mul_i32 s100, s100, 0x1e0
	s_addk_i32 s100, 0x101
	s_add_i32 s100, s100, s99
	s_mov_b32 s83, s100
	s_add_i32 s99, s100, 1
	s_mov_b32 s98, 3
	s_branch .Lp1be_entry
.Lp1be_done:
	s_mov_b32 s98, 0
	s_branch .LBB0_495

.LBB0_547:
	s_or_b64 exec, exec, s[0:1]
	s_mov_b32 s98, 0
	s_movk_i32 s99, 0x600
	s_movk_i32 s100, 0x5ff
	s_cmpk_lg_u32 s80, 0x100
	s_cbranch_scc1 .Lp1be_entry
	s_movk_i32 s99, 0x400
	s_movk_i32 s100, 0x3ff
	s_and_b32 s101, s83, 1
	s_cmp_eq_u32 s101, 0
	s_cbranch_scc1 .Lp1be_entry
	s_cmpk_gt_u32 s83, 31
	s_cbranch_scc1 .Lp1be_entry
	s_movk_i32 s80, 0x200

.LBB0_567:
	s_cmp_lg_u32 s98, 0
	s_cbranch_scc1 .Lp1be_ret
	v_readlane_b32 s80, v254, 59
	s_cmpk_lg_u32 s80, 0x100
	s_cbranch_scc1 .Lp3be_skip
	s_and_b32 s101, s83, 1
	s_cmp_eq_u32 s101, 0
	s_cbranch_scc1 .Lp3be_skip
	s_cmpk_gt_u32 s83, 31
	s_cbranch_scc1 .Lp3be_skip
	s_mov_b32 s98, 2
	s_lshr_b32 s83, s83, 1
	s_addk_i32 s83, 0x200
	s_movk_i32 s99, 0x210
	s_movk_i32 s100, 0x20f
	s_branch .Lp3be_entry
.Lp3be_ret:
	v_readlane_b32 s83, v255, 6
	s_mov_b32 s98, 0

.LBB0_619:
	s_or_b64 exec, exec, s[0:1]
	s_movk_i32 s99, 0x210
	s_movk_i32 s100, 0x20f
	s_cmpk_lg_u32 s80, 0x100
	s_cbranch_scc1 .Lp3be_entry
	s_movk_i32 s99, 0x200
	s_movk_i32 s100, 0x1ff
.Lp3be_entry:
	s_add_u32 s6, s74, 0x300000
	s_addc_u32 s7, s75, 0
	s_add_u32 s0, s74, 0xee00000
	s_addc_u32 s1, s75, 0
	v_mov_b32_e32 v9, v179
	s_cmp_lt_u32 s83, s99
	s_waitcnt lgkmcnt(0)
	s_barrier
	s_cselect_b64 s[8:9], -1, 0
	s_cmp_gt_u32 s83, s100
	v_readfirstlane_b32 s2, v9
	s_cbranch_scc1 .LBB0_635
	v_lshlrev_b32_e32 v0, 4, v9
	v_add_u32_e32 v1, 0x2000, v0
	v_ashrrev_i32_e32 v2, 31, v1
	v_lshrrev_b32_e32 v2, 22, v2
	v_add_u32_e32 v2, v1, v2
	v_ashrrev_i32_e32 v8, 10, v2
	v_mul_i32_i24_e32 v2, 0x400, v8
	v_sub_u32_e32 v1, v1, v2
	v_lshrrev_b32_e32 v2, 4, v1
	v_bitop3_b32 v1, v2, v1, 32 bitop3:0x6c
	v_ashrrev_i32_e32 v2, 31, v1
	v_lshrrev_b32_e32 v2, 26, v2
	v_add_u32_e32 v2, v1, v2
	v_lshlrev_b32_e32 v3, 3, v8
	v_ashrrev_i32_e32 v10, 6, v2
	v_and_b32_e32 v3, -16, v3
	v_add_u32_e32 v3, v10, v3
	v_and_b32_e32 v4, 3, v10
	s_mov_b32 s10, 0xfffe0
	v_lshrrev_b32_e32 v5, 2, v3
	v_lshlrev_b32_e32 v6, 1, v3
	v_and_b32_e32 v2, 0xc0, v2
	v_and_or_b32 v4, v3, s10, v4
	v_and_b32_e32 v5, 4, v5
	v_and_b32_e32 v6, 24, v6
	v_sub_u32_e32 v1, v1, v2
	v_mov_b32_e32 v2, 1
	v_or3_b32 v4, v4, v5, v6
	v_lshlrev_b32_e32 v5, 5, v8
	v_ashrrev_i16_sdwa v1, v2, sext(v1) dst_sel:DWORD dst_unused:UNUSED_PAD src0_sel:DWORD src1_sel:BYTE_0
	v_and_b32_e32 v5, 32, v5
	v_bfe_i32 v11, v1, 0, 16
	v_add_lshl_u32 v1, v5, v11, 1
	v_lshl_add_u32 v128, v4, 12, v1
	v_lshl_add_u32 v130, v3, 12, v1
	v_bfe_i32 v1, v9, 27, 1
	v_lshrrev_b32_e32 v1, 22, v1
	v_add_u32_e32 v1, v0, v1
	v_and_b32_e32 v1, 0xfffffc00, v1
	v_sub_u32_e32 v0, v0, v1
	v_lshrrev_b32_e32 v1, 4, v0
	v_ashrrev_i32_e32 v3, 31, v9
	v_bitop3_b32 v0, v1, v0, 32 bitop3:0x6c
	v_lshrrev_b32_e32 v3, 26, v3
	v_ashrrev_i32_e32 v1, 31, v0
	v_add_u32_e32 v3, v9, v3
	v_lshrrev_b32_e32 v1, 26, v1
	v_ashrrev_i32_e32 v13, 6, v3
	v_add_u32_e32 v1, v0, v1
	v_lshlrev_b32_e32 v3, 3, v13
	v_ashrrev_i32_e32 v12, 6, v1
	v_and_b32_e32 v3, -16, v3
	v_add_u32_e32 v3, v12, v3
	v_and_b32_e32 v4, 3, v12
	v_and_or_b32 v4, v3, s10, v4
	s_and_b32 s10, s83, 7
	s_lshr_b32 s11, s83, 3
	s_mulk_i32 s10, 0x42
	s_add_i32 s10, s10, s11
	s_lshr_b32 s11, s10, 2
	s_and_b32 s13, s11, 0xf8
	s_sub_i32 s11, 0x84, s13
	v_lshrrev_b32_e32 v5, 2, v3
	v_lshlrev_b32_e32 v6, 1, v3
	v_and_b32_e32 v1, 0xc0, v1
	s_min_u32 s14, s11, 8
	v_and_b32_e32 v5, 4, v5
	v_and_b32_e32 v6, 24, v6
	v_sub_u32_e32 v0, v0, v1
	v_cvt_f32_ubyte0_e32 v1, s14
	v_or3_b32 v4, v4, v5, v6
	v_lshlrev_b32_e32 v5, 5, v13
	v_ashrrev_i16_sdwa v0, v2, sext(v0) dst_sel:DWORD dst_unused:UNUSED_PAD src0_sel:DWORD src1_sel:BYTE_0
	v_rcp_iflag_f32_e32 v2, v1
	v_and_b32_e32 v5, 32, v5
	v_bfe_i32 v14, v0, 0, 16
	v_add_lshl_u32 v0, v5, v14, 1
	s_and_b32 s15, s10, 31
	v_lshl_add_u32 v132, v4, 12, v0
	v_cvt_f32_ubyte0_e32 v4, s15
	v_mul_f32_e32 v2, v4, v2
	v_trunc_f32_e32 v2, v2
	v_cvt_u32_f32_e32 v5, v2
	s_ashr_i32 s12, s2, 6
	v_lshl_add_u32 v134, v3, 12, v0
	v_fma_f32 v0, -v2, v1, v4
	s_ashr_i32 s3, s2, 8
	s_lshl_b32 s30, s12, 10
	v_cmp_ge_f32_e64 s[10:11], |v0|, v1
	v_readfirstlane_b32 s16, v5
	s_cmp_lg_u64 s[10:11], 0
	s_addc_u32 s10, s16, 0
	s_mul_i32 s11, s10, s14
	s_sub_i32 s11, s15, s11
	s_and_b32 s11, s11, 0xff
	s_add_i32 s45, s13, s11
	s_and_b32 s11, s45, 0x8a
	s_cmp_eq_u32 s11, 0
	s_cselect_b32 s11, 16, 0
	s_xor_b32 s45, s45, s11
	s_and_b32 s46, s10, 0xff
	s_lshl_b32 s13, s45, 20
	s_lshl_b32 s10, s46, 20
	s_add_u32 s26, s6, s10
	s_addc_u32 s27, s7, 0
	s_add_i32 s31, s30, 0
	s_add_i32 m0, s31, 0x10000
	v_readlane_b32 s48, v254, 32
	global_load_lds_dwordx4 v132, s[26:27]
	s_add_i32 m0, s31, 0x12000
	s_add_u32 s10, s26, 0x80000
	global_load_lds_dwordx4 v128, s[26:27]
	s_addc_u32 s11, s27, 0
	s_add_i32 m0, s31, 0x14000
	v_readlane_b32 s62, v254, 46
	global_load_lds_dwordx4 v132, s[10:11]
	s_add_i32 m0, s31, 0x16000
	v_readlane_b32 s63, v254, 47
	s_add_u32 s24, s62, s13
	s_addc_u32 s25, s63, 0
	s_add_i32 s33, s31, 0x2000
	global_load_lds_dwordx4 v128, s[10:11]
	s_mov_b32 m0, s31
	s_add_u32 s10, s24, 0x80000
	global_load_lds_dwordx4 v134, s[24:25]
	s_mov_b32 m0, s33
	s_addc_u32 s11, s25, 0
	s_add_i32 s34, s31, 0x4000
	global_load_lds_dwordx4 v130, s[24:25]
	s_mov_b32 m0, s34
	s_add_i32 s35, s31, 0x6000
	global_load_lds_dwordx4 v134, s[10:11]
	s_mov_b32 m0, s35
	v_mov_b32_e32 v133, 0
	global_load_lds_dwordx4 v130, s[10:11]
	v_mov_b32_e32 v129, v133
	v_mov_b32_e32 v135, v133
	v_mov_b32_e32 v131, v133
	s_cmp_eq_u32 s3, 1
	s_mov_b32 s36, 0
	v_lshl_add_u64 v[6:7], s[26:27], 0, v[132:133]
	v_lshl_add_u64 v[4:5], s[26:27], 0, v[128:129]
	v_lshl_add_u64 v[0:1], s[24:25], 0, v[134:135]
	s_cselect_b64 s[10:11], -1, 0
	s_cmp_lg_u32 s3, 1
	v_lshl_add_u64 v[2:3], s[24:25], 0, v[130:131]
	v_readlane_b32 s49, v254, 33
	v_readlane_b32 s50, v254, 34
	v_readlane_b32 s51, v254, 35
	v_readlane_b32 s52, v254, 36
	v_readlane_b32 s53, v254, 37
	v_readlane_b32 s54, v254, 38
	v_readlane_b32 s55, v254, 39
	v_readlane_b32 s56, v254, 40
	v_readlane_b32 s57, v254, 41
	v_readlane_b32 s58, v254, 42
	v_readlane_b32 s59, v254, 43
	v_readlane_b32 s60, v254, 44
	v_readlane_b32 s61, v254, 45
	s_cbranch_scc1 .LBB0_622
	s_barrier
.LBB0_622:
	s_add_u32 s37, s74, 0x1b800000
	s_addc_u32 s38, s75, 0
	s_lshl_b32 s12, s12, 5
	s_and_b32 s17, s12, 0x60
	s_mov_b64 s[12:13], 0x80
	s_add_i32 m0, s31, 0x18000
	v_lshl_add_u64 v[6:7], v[6:7], 0, s[12:13]
	s_lshl_b32 s16, s3, 13
	s_lshl_b32 s18, s17, 7
	s_waitcnt vmcnt(2)
	s_barrier
	global_load_lds_dwordx4 v[6:7], off
	v_lshl_add_u64 v[4:5], v[4:5], 0, s[12:13]
	s_add_i32 m0, s31, 0x1a000
	s_add_i32 s39, s31, 0x8000
	s_add_i32 s40, s31, 0xa000
	global_load_lds_dwordx4 v[4:5], off
	v_lshl_add_u64 v[0:1], v[0:1], 0, s[12:13]
	s_mov_b32 m0, s39
	s_add_u32 s14, s26, 0x80080
	global_load_lds_dwordx4 v[0:1], off
	v_lshl_add_u64 v[0:1], v[2:3], 0, s[12:13]
	s_mov_b32 m0, s40
	s_addc_u32 s15, s27, 0
	global_load_lds_dwordx4 v[0:1], off
	s_add_i32 m0, s31, 0x1c000
	v_lshl_add_u64 v[0:1], s[14:15], 0, v[132:133]
	global_load_lds_dwordx4 v[0:1], off
	v_lshl_add_u64 v[0:1], s[14:15], 0, v[128:129]
	s_add_i32 m0, s31, 0x1e000
	s_cmpk_lt_u32 s2, 0x100
	global_load_lds_dwordx4 v[0:1], off
	v_lshrrev_b32_e32 v1, 1, v9
	v_and_b32_e32 v1, 24, v1
	v_and_b32_e32 v0, 15, v9
	v_lshlrev_b32_e32 v2, 1, v1
	v_lshl_or_b32 v154, s3, 6, v0
	v_lshl_or_b32 v0, v0, 6, v2
	v_lshlrev_b32_e32 v2, 2, v9
	v_and_b32_e32 v2, 32, v2
	v_bitop3_b32 v3, v0, s16, v2 bitop3:0xde
	v_bitop3_b32 v155, v0, s18, v2 bitop3:0xde
	v_lshlrev_b32_e32 v0, 15, v13
	v_and_b32_e32 v0, 0xffff0000, v0
	v_or_b32_e32 v156, s17, v1
	v_lshl_add_u32 v0, v12, 12, v0
	v_and_b32_e32 v1, 1, v13
	v_lshl_or_b32 v0, v1, 6, v0
	v_lshl_add_u32 v136, v14, 1, v0
	v_lshlrev_b32_e32 v0, 15, v8
	v_and_b32_e32 v0, 0xffff0000, v0
	s_waitcnt vmcnt(6)
	v_lshl_add_u32 v0, v10, 12, v0
	v_and_b32_e32 v1, 1, v8
	s_cselect_b64 s[14:15], -1, 0
	v_lshl_or_b32 v0, v1, 6, v0
	s_add_i32 s43, 0, 0x10000
	s_add_i32 s44, 0, 0x14000
	s_ashr_i32 s41, s80, 31
	s_mov_b32 s42, s80
	v_mov_b32_e32 v137, v133
	v_lshl_add_u32 v138, v11, 1, v0
	v_mov_b32_e32 v139, v133
	v_mov_b32_e32 v140, s99
	v_mov_b32_e32 v141, 0
	v_mov_b32_e32 v142, s100
	v_mov_b32_e32 v143, 0
	v_add_u32_e32 v157, s43, v155
	v_add_u32_e32 v158, s44, v155
	v_add_u32_e32 v159, 0, v3
	s_barrier
	s_branch .LBB0_625

.LBB0_625:
	s_add_i32 s36, s36, 1
	s_mul_i32 s2, s36, s41
	s_mul_hi_u32 s3, s36, s42
	s_add_i32 s3, s3, s2
	s_mul_i32 s2, s36, s42
	s_add_u32 s20, s2, s83
	s_addc_u32 s21, s3, 0
	v_cmp_gt_i64_e32 vcc, s[20:21], v[142:143]
	v_cmp_lt_i64_e64 s[2:3], s[20:21], v[140:141]
	s_cbranch_vccnz .LBB0_627
	s_ashr_i32 s16, s20, 31
	s_lshr_b32 s16, s16, 29
	s_add_i32 s16, s20, s16
	s_ashr_i32 s17, s16, 3
	s_and_b32 s16, s16, -8
	s_sub_i32 s16, s20, s16
	s_cmp_lt_i32 s16, 0
	s_movk_i32 s18, 0x43
	s_cselect_b32 s18, s18, 0x42
	s_mul_i32 s16, s16, s18
	s_add_i32 s16, s16, s17
	s_ashr_i32 s17, s16, 31
	s_lshr_b32 s17, s17, 27
	s_add_i32 s17, s16, s17
	s_ashr_i32 s18, s17, 5
	s_lshl_b32 s18, s18, 3
	s_sub_i32 s19, 0x84, s18
	s_min_i32 s19, s19, 8
	s_abs_i32 s20, s19
	v_cvt_f32_u32_e32 v0, s20
	s_sub_i32 s22, 0, s20
	s_andn2_b32 s17, s17, 31
	s_sub_i32 s17, s16, s17
	v_rcp_iflag_f32_e32 v0, v0
	s_abs_i32 s16, s17
	s_xor_b32 s21, s17, s19
	s_ashr_i32 s21, s21, 31
	v_mul_f32_e32 v0, 0x4f7ffffe, v0
	v_cvt_u32_f32_e32 v0, v0
	s_nop 0
	v_readfirstlane_b32 s23, v0
	s_mul_i32 s22, s22, s23
	s_mul_hi_u32 s22, s23, s22
	s_add_i32 s23, s23, s22
	s_mul_hi_u32 s22, s16, s23
	s_mul_i32 s23, s22, s20
	s_sub_i32 s16, s16, s23
	s_add_i32 s28, s22, 1
	s_sub_i32 s23, s16, s20
	s_cmp_ge_u32 s16, s20
	s_cselect_b32 s22, s28, s22
	s_cselect_b32 s16, s23, s16
	s_add_i32 s23, s22, 1
	s_cmp_ge_u32 s16, s20
	s_cselect_b32 s16, s23, s22
	s_xor_b32 s16, s16, s21
	s_sub_i32 s16, s16, s21
	s_mul_i32 s19, s16, s19
	s_sub_i32 s17, s17, s19
	s_add_i32 s18, s18, s17
	s_and_b32 s19, s18, 0x8a
	s_cmp_eq_u32 s19, 0
	s_cselect_b32 s19, 16, 0
	s_xor_b32 s18, s18, s19

.LBB0_635:
	s_cmp_eq_u32 s98, 2
	s_cbranch_scc1 .Lp3be_ret
	s_cmpk_eq_i32 s80, 0x100
	s_cselect_b32 s33, 16, 0
	v_mov_b32_e32 v0, v179
	s_cmp_ge_i32 s83, s33
	s_cselect_b64 s[4:5], -1, 0
	s_cmp_lt_i32 s83, s33
	v_readfirstlane_b32 s2, v0
	s_cbranch_scc1 .LBB0_654
	s_sub_i32 s3, s83, s33
	s_ashr_i32 s2, s2, 6
	s_lshl_b32 s3, s3, 3
	s_add_i32 s28, s2, s3
	s_cmpk_gt_i32 s28, 0x41f
	s_cbranch_scc1 .LBB0_654
	s_sub_i32 s2, s80, s33
	s_lshl_b32 s29, s2, 3
	v_readlane_b32 s12, v254, 16
	v_readlane_b32 s13, v254, 17
	s_add_u32 s10, s12, 0x1000
	s_addc_u32 s11, s13, 0
	s_add_u32 s12, s12, 0x2000
	s_addc_u32 s13, s13, 0
	v_readlane_b32 s14, v254, 18
	v_readlane_b32 s15, v254, 19
	s_add_u32 s30, s74, 0x17203800
	s_addc_u32 s31, s75, 0
	s_lshl_b32 s14, s80, 12
	s_lshl_b32 s15, s33, 12
	v_readlane_b32 s36, v254, 32
	s_lshl_b32 s34, s28, 9
	s_sub_i32 s35, s14, s15
	v_readlane_b32 s50, v254, 46
	v_lshlrev_b32_e32 v0, 3, v0
	v_readlane_b32 s16, v254, 20
	v_readlane_b32 s17, v254, 21
	v_readlane_b32 s18, v254, 22
	v_readlane_b32 s19, v254, 23
	v_readlane_b32 s37, v254, 33
	v_readlane_b32 s38, v254, 34
	v_readlane_b32 s39, v254, 35
	v_readlane_b32 s40, v254, 36
	v_readlane_b32 s41, v254, 37
	v_readlane_b32 s42, v254, 38
	v_readlane_b32 s43, v254, 39
	v_readlane_b32 s44, v254, 40
	v_readlane_b32 s45, v254, 41
	v_readlane_b32 s51, v254, 47
	s_add_u32 s36, s50, 0xfffc8000
	v_and_b32_e32 v74, 0x1f8, v0
	s_mov_b64 s[2:3], 0x1000
	s_addc_u32 s37, s51, -1
	v_mov_b32_e32 v65, 0
	s_mov_b32 s15, 0
	s_mov_b32 s38, 0x94e0000
	s_mov_b32 s39, 0xe8dfd000
	s_movk_i32 s40, 0xd000
	s_mov_b32 s41, 0xe8dfe000
	s_movk_i32 s42, 0xe000
	s_mov_b32 s43, 0xe8dff000
	s_movk_i32 s44, 0xf000
	s_mov_b32 s45, 0xe8e00000
	s_mov_b64 s[16:17], 0x4000
	s_mov_b64 s[18:19], 0x8000
	v_readlane_b32 s20, v254, 24
	v_readlane_b32 s21, v254, 25
	v_readlane_b32 s22, v254, 26
	v_readlane_b32 s23, v254, 27
	v_readlane_b32 s24, v254, 28
	v_readlane_b32 s25, v254, 29
	v_readlane_b32 s26, v254, 30
	v_readlane_b32 s27, v254, 31
	v_readlane_b32 s46, v254, 42
	v_readlane_b32 s47, v254, 43
	v_readlane_b32 s48, v254, 44
	v_readlane_b32 s49, v254, 45
	s_branch .LBB0_639
